# speedup vs baseline: 1.0094x; 1.0071x over previous
; __device__ __forceinline__ u16 f2bf(float x) { return (u16)(cvtpk(x, 0.f) & 0xffffu); }
; __device__ __forceinline__ float bf2f(u16 x) { return __uint_as_float(((unsigned)x) << 16); }
; __device__ __forceinline__ int opaque_tid() { int t = threadIdx.x; asm volatile("" : "+v"(t)); return t; }
; template <int DQK, int ldq, int ldk, int ldo> ...
;     ...
;   const int tid = opaque_tid(), wid = __builtin_amdgcn_readfirstlane(tid >> 6), lane = tid & 63, r32 = lane & 31, hi = lane >> 5;
;   char* V_lds = lds; char* K_lds = lds + 2 * SHM_V;
;   float* wsl = (float*)(lds + 2 * SHM_V + 2 * SHM_K) + wid * 64; float* li_l = wsl; float* al_l = wsl + 32;
;   float m_reg = -1e30f, l_reg = 0; f32x16 o[4] = {}; bf16x8 qr[ND];
;   const u16* Qw = Qb + (long)(wid * 32 + r32) * ldq + hi * 8;
; #pragma unroll
;   for (int d0 = 0; d0 < ND; ++d0) qr[d0] = *reinterpret_cast<const bf16x8*>(Qw + d0 * 16);
;   if constexpr (DQK == 192) {
;     const int pos = pos0 + wid * 32 + r32;
; #pragma unroll
;     for (int hh = 0; hh < 2; ++hh) {
;       const float* cp = ropeC + pos * 32 + hh * 16 + hi * 8; const float* sp = ropeS + pos * 32 + hh * 16 + hi * 8;
;       bf16x8 x1 = qr[8 + hh], x2 = qr[10 + hh]; bf16x8 y1, y2;
; #pragma unroll
;       for (int t = 0; t < 8; ++t) {
;         float a = bf2f((u16)x1[t]), b = bf2f((u16)x2[t]), c = cp[t], s = sp[t];
;         y1[t] = (short)f2bf(a * c - b * s); y2[t] = (short)f2bf(a * s + b * c);
;       }
;       qr[8 + hh] = y1; qr[10 + hh] = y2;
;     }
;   }
.LBB0_487:
	s_sub_i32 s0, s7, s16
	s_cmp_ge_u32 s7, s16
	s_cselect_b32 s0, s0, s7
	s_xor_b32 s0, s0, s6
	s_sub_i32 s6, s0, s6
	s_ashr_i32 s0, s8, 3
	s_ashr_i32 s1, s0, 31
	v_readlane_b32 s7, v252, 24
	s_lshl_b64 s[58:59], s[0:1], s7
	s_lshl_b32 s7, s6, 8
	s_and_b32 s13, s8, 7
	s_ashr_i32 s0, s7, 31
	s_add_u32 s10, s58, s7
	s_addc_u32 s11, s59, s0
	s_lshl_b64 s[0:1], s[58:59], 12
	v_readlane_b32 s6, v254, 8
	s_add_u32 s8, s6, s0
	v_readlane_b32 s6, v254, 9
	s_addc_u32 s9, s6, s1
	s_lshl_b32 s6, s13, 9
	s_add_u32 s8, s8, s6
	s_mul_i32 s12, s11, 0xc00
	s_mul_hi_u32 s14, s10, 0xc00
	s_addc_u32 s9, s9, 0
	s_add_i32 s14, s14, s12
	s_mul_i32 s12, s10, 0xc00
	v_readlane_b32 s15, v253, 62
	s_add_u32 s12, s15, s12
	v_readlane_b32 s15, v253, 63
	s_addc_u32 s14, s15, s14
	s_mul_i32 s15, s13, 0x180
	s_add_u32 s60, s12, s15
	s_addc_u32 s61, s14, 0
	s_lshl_b64 s[64:65], s[58:59], 7
	v_readlane_b32 s12, v254, 2
	s_add_u32 s80, s12, s64
	v_readlane_b32 s12, v254, 3
	v_mov_b32_e32 v23, v181
	s_barrier
	s_addc_u32 s81, s12, s65
	v_mov_b64_e32 v[2:3], s[60:61]
	v_readfirstlane_b32 s12, v23
	s_and_b32 s14, s12, 0x3fffffc0
	s_lshl_b32 s14, s14, 2
	s_add_i32 s31, s14, 16
	s_ashr_i32 s14, s12, 1
	s_and_b32 s12, s14, 0xffffffe0
	v_mov_b32_e32 v0, s14
	s_movk_i32 s14, 0xffe0
	v_and_b32_e32 v194, 31, v23
	v_bfi_b32 v0, s14, v0, v23
	s_movk_i32 s14, 0xc00
	v_mad_i64_i32 v[2:3], s[58:59], v0, s14, v[2:3]
	v_or_b32_e32 v0, s7, v194
	v_add_lshl_u32 v18, v0, s12, 5
	v_ashrrev_i32_e32 v19, 31, v18
	v_readlane_b32 s14, v253, 38
	v_lshlrev_b64 v[20:21], 2, v[18:19]
	v_readlane_b32 s15, v253, 39
	v_bfe_u32 v193, v23, 5, 1
	v_lshlrev_b32_e32 v182, 4, v193
	v_lshl_add_u64 v[18:19], s[14:15], 0, v[20:21]
	v_readlane_b32 s14, v253, 40
	v_mov_b32_e32 v183, v1
	v_and_b32_e32 v0, 32, v23
	v_readlane_b32 s15, v253, 41
	v_lshl_add_u64 v[6:7], v[2:3], 0, v[182:183]
	v_lshl_add_u64 v[18:19], v[18:19], 0, v[0:1]
	v_lshl_add_u64 v[20:21], s[14:15], 0, v[20:21]
	global_load_dwordx4 v[112:115], v[6:7], off
	global_load_dwordx4 v[116:119], v[6:7], off offset:32
	global_load_dwordx4 v[120:123], v[6:7], off offset:64
	global_load_dwordx4 v[124:127], v[6:7], off offset:96
	global_load_dwordx4 v[128:131], v[6:7], off offset:128
	global_load_dwordx4 v[132:135], v[6:7], off offset:160
	global_load_dwordx4 v[136:139], v[6:7], off offset:192
	global_load_dwordx4 v[140:143], v[6:7], off offset:224
	global_load_dwordx4 v[10:13], v[6:7], off offset:256
	global_load_dwordx4 v[2:5], v[6:7], off offset:288
	global_load_dwordx4 v[14:17], v[6:7], off offset:320
	s_nop 0
	global_load_dwordx4 v[6:9], v[6:7], off offset:352
	v_lshl_add_u64 v[20:21], v[20:21], 0, v[0:1]
	global_load_dwordx4 v[72:75], v[18:19], off
	global_load_dwordx4 v[76:79], v[18:19], off offset:16
	global_load_dwordx4 v[80:83], v[18:19], off offset:64
	global_load_dwordx4 v[84:87], v[18:19], off offset:80
	global_load_dwordx4 v[88:91], v[20:21], off
	global_load_dwordx4 v[92:95], v[20:21], off offset:16
	global_load_dwordx4 v[96:99], v[20:21], off offset:64
	global_load_dwordx4 v[100:103], v[20:21], off offset:80
	v_ashrrev_i32_e32 v64, 4, v23
	v_lshlrev_b32_e32 v65, 3, v23
	v_and_b32_e32 v22, 63, v23
	s_add_i32 s31, s31, 0x14000
	v_ashrrev_i32_e32 v69, 3, v23
	v_and_b32_e32 v70, 56, v65
	s_cmp_lg_u32 16, -1
	s_movk_i32 s15, 0x180
	s_movk_i32 s14, 0x70
	s_cselect_b32 s7, 16, 0
	s_add_u32 s60, s8, 0x40100
	s_addc_u32 s61, s9, 0
	v_mad_u32_u24 v200, v194, s15, 16
	v_bitop3_b32 v203, v182, v65, s14 bitop3:0x78
	s_mov_b32 s58, 0
	v_lshl_add_u32 v211, v194, 2, s31
	v_add_u32_e32 v214, 0xe000, v200
	v_mov_b32_e32 v217, 0xf149f2ca
	v_mov_b32_e32 v216, 0
	s_waitcnt vmcnt(0)
	v_lshlrev_b32_e32 v28, 16, v10
	s_waitcnt vmcnt(3)
	v_lshlrev_b32_e32 v29, 16, v14
	s_waitcnt vmcnt(1)
	v_mov_b32_e32 v26, v72
	v_mov_b32_e32 v31, v26
	s_waitcnt vmcnt(0)
	v_mov_b32_e32 v27, v88
	v_pk_mul_f32 v[24:25], v[26:27], v[28:29]
	v_mov_b32_e32 v30, v27
	v_sub_f32_e32 v0, v24, v25
	v_pk_mul_f32 v[26:27], v[30:31], v[28:29]
	v_cvt_pk_bf16_f32 v24, v0, v1
	v_and_b32_e32 v29, 0xffff0000, v10
	v_add_f32_e32 v0, v26, v27
	v_cvt_pk_bf16_f32 v25, v0, v1
	v_and_b32_e32 v28, 0xffff0000, v14
	s_waitcnt vmcnt(0)
	v_mov_b32_e32 v27, v73
	v_mov_b32_e32 v26, v89
	v_pk_mul_f32 v[30:31], v[26:27], v[28:29]
	s_nop 0
	v_sub_f32_e32 v0, v31, v30
	v_mov_b32_e32 v30, v27
	v_mov_b32_e32 v31, v26
	v_pk_mul_f32 v[26:27], v[30:31], v[28:29]
	v_cvt_pk_bf16_f32 v10, v0, v1
	v_lshlrev_b32_e32 v31, 16, v11
	v_add_f32_e32 v0, v26, v27
	v_cvt_pk_bf16_f32 v14, v0, v1
	v_lshlrev_b32_e32 v30, 16, v15
	s_waitcnt vmcnt(1)
	v_mov_b32_e32 v29, v74
	v_mov_b32_e32 v32, v29
	s_waitcnt vmcnt(0)
	v_mov_b32_e32 v28, v90
	v_pk_mul_f32 v[26:27], v[28:29], v[30:31]
	v_mov_b32_e32 v33, v28
	v_sub_f32_e32 v0, v27, v26
	v_pk_mul_f32 v[28:29], v[32:33], v[30:31]
	v_cvt_pk_bf16_f32 v26, v0, v1
	v_and_b32_e32 v31, 0xffff0000, v11
	v_add_f32_e32 v0, v28, v29
	v_cvt_pk_bf16_f32 v27, v0, v1
	v_and_b32_e32 v30, 0xffff0000, v15
	s_waitcnt vmcnt(0)
	v_mov_b32_e32 v29, v75
	v_mov_b32_e32 v28, v91
	v_pk_mul_f32 v[32:33], v[28:29], v[30:31]
	s_nop 0
	v_sub_f32_e32 v0, v33, v32
	v_mov_b32_e32 v32, v29
	v_mov_b32_e32 v33, v28
	v_pk_mul_f32 v[28:29], v[32:33], v[30:31]
	v_cvt_pk_bf16_f32 v11, v0, v1
	v_lshlrev_b32_e32 v33, 16, v12
	v_add_f32_e32 v0, v28, v29
	v_cvt_pk_bf16_f32 v15, v0, v1
	v_lshlrev_b32_e32 v32, 16, v16
	s_waitcnt vmcnt(1)
	v_mov_b32_e32 v31, v76
	v_mov_b32_e32 v34, v31
	s_waitcnt vmcnt(0)
	v_mov_b32_e32 v30, v92
	v_pk_mul_f32 v[28:29], v[30:31], v[32:33]
	v_mov_b32_e32 v35, v30
	v_sub_f32_e32 v0, v29, v28
	v_pk_mul_f32 v[30:31], v[34:35], v[32:33]
	v_cvt_pk_bf16_f32 v28, v0, v1
	v_and_b32_e32 v33, 0xffff0000, v12
	v_add_f32_e32 v0, v30, v31
	v_cvt_pk_bf16_f32 v29, v0, v1
	v_and_b32_e32 v32, 0xffff0000, v16
	s_waitcnt vmcnt(0)
; __device__ __forceinline__ u16 f2bf(float x) { return (u16)(cvtpk(x, 0.f) & 0xffffu); }
; __device__ __forceinline__ float bf2f(u16 x) { return __uint_as_float(((unsigned)x) << 16); }
; template <int DQK, int ldq, int ldk, int ldo> ...
;     ...
;     for (int hh = 0; hh < 2; ++hh) {
;       const float* cp = ropeC + pos * 32 + hh * 16 + hi * 8; const float* sp = ropeS + pos * 32 + hh * 16 + hi * 8;
;       bf16x8 x1 = qr[8 + hh], x2 = qr[10 + hh]; bf16x8 y1, y2;
; #pragma unroll
;       for (int t = 0; t < 8; ++t) {
;         float a = bf2f((u16)x1[t]), b = bf2f((u16)x2[t]), c = cp[t], s = sp[t];
;         y1[t] = (short)f2bf(a * c - b * s); y2[t] = (short)f2bf(a * s + b * c);
;       }
;       qr[8 + hh] = y1; qr[10 + hh] = y2;
;     }
	v_mov_b32_e32 v31, v77
	v_mov_b32_e32 v30, v93
	v_pk_mul_f32 v[34:35], v[30:31], v[32:33]
	s_nop 0
	v_sub_f32_e32 v0, v35, v34
	v_mov_b32_e32 v34, v31
	v_mov_b32_e32 v35, v30
	v_pk_mul_f32 v[30:31], v[34:35], v[32:33]
	v_cvt_pk_bf16_f32 v12, v0, v1
	v_lshlrev_b32_e32 v35, 16, v13
	v_add_f32_e32 v0, v30, v31
	v_cvt_pk_bf16_f32 v16, v0, v1
	v_lshlrev_b32_e32 v34, 16, v17
	s_waitcnt vmcnt(1)
	v_mov_b32_e32 v33, v78
	v_mov_b32_e32 v36, v33
	s_waitcnt vmcnt(0)
	v_mov_b32_e32 v32, v94
	v_pk_mul_f32 v[30:31], v[32:33], v[34:35]
	v_mov_b32_e32 v37, v32
	v_sub_f32_e32 v0, v31, v30
	v_pk_mul_f32 v[32:33], v[36:37], v[34:35]
	v_cvt_pk_bf16_f32 v30, v0, v1
	v_and_b32_e32 v35, 0xffff0000, v13
	v_add_f32_e32 v0, v32, v33
	v_cvt_pk_bf16_f32 v31, v0, v1
	v_and_b32_e32 v34, 0xffff0000, v17
	s_waitcnt vmcnt(0)
	v_mov_b32_e32 v33, v79
	v_mov_b32_e32 v32, v95
	v_pk_mul_f32 v[36:37], v[32:33], v[34:35]
	s_nop 0
	v_sub_f32_e32 v0, v37, v36
	v_mov_b32_e32 v36, v33
	v_mov_b32_e32 v37, v32
	v_pk_mul_f32 v[32:33], v[36:37], v[34:35]
	v_cvt_pk_bf16_f32 v13, v0, v1
	v_lshlrev_b32_e32 v37, 16, v2
	v_add_f32_e32 v0, v32, v33
	v_cvt_pk_bf16_f32 v17, v0, v1
	v_lshlrev_b32_e32 v36, 16, v6
	s_waitcnt vmcnt(1)
	v_mov_b32_e32 v35, v80
	v_mov_b32_e32 v38, v35
	s_waitcnt vmcnt(0)
	v_mov_b32_e32 v34, v96
	v_pk_mul_f32 v[32:33], v[34:35], v[36:37]
	v_mov_b32_e32 v39, v34
	v_sub_f32_e32 v0, v33, v32
	v_pk_mul_f32 v[34:35], v[38:39], v[36:37]
	v_cvt_pk_bf16_f32 v32, v0, v1
	v_and_b32_e32 v39, 0xffff0000, v2
	v_add_f32_e32 v0, v34, v35
	v_cvt_pk_bf16_f32 v33, v0, v1
	v_and_b32_e32 v38, 0xffff0000, v6
	v_and_b32_e32 v2, 0xffff0000, v7
	s_waitcnt vmcnt(1)
	v_mov_b32_e32 v37, v81
	v_mov_b32_e32 v40, v37
	s_waitcnt vmcnt(0)
	v_mov_b32_e32 v36, v97
	v_pk_mul_f32 v[34:35], v[36:37], v[38:39]
	v_mov_b32_e32 v41, v36
	v_sub_f32_e32 v0, v35, v34
	v_pk_mul_f32 v[36:37], v[40:41], v[38:39]
	v_cvt_pk_bf16_f32 v34, v0, v1
	v_lshlrev_b32_e32 v41, 16, v3
	v_add_f32_e32 v0, v36, v37
	v_cvt_pk_bf16_f32 v35, v0, v1
	v_lshlrev_b32_e32 v40, 16, v7
	v_and_b32_e32 v3, 0xffff0000, v3
	s_waitcnt vmcnt(1)
	v_mov_b32_e32 v39, v82
	v_mov_b32_e32 v42, v39
	s_waitcnt vmcnt(0)
	v_mov_b32_e32 v38, v98
	v_pk_mul_f32 v[36:37], v[38:39], v[40:41]
	v_mov_b32_e32 v43, v38
	v_sub_f32_e32 v0, v37, v36
	v_pk_mul_f32 v[38:39], v[42:43], v[40:41]
	v_cvt_pk_bf16_f32 v36, v0, v1
	s_nop 0
	v_add_f32_e32 v0, v38, v39
	v_cvt_pk_bf16_f32 v37, v0, v1
	s_waitcnt vmcnt(0)
	v_mov_b32_e32 v41, v83
	v_mov_b32_e32 v40, v99
	v_pk_mul_f32 v[6:7], v[40:41], v[2:3]
	s_nop 0
	v_sub_f32_e32 v0, v7, v6
	v_mov_b32_e32 v6, v41
	v_mov_b32_e32 v7, v40
	v_pk_mul_f32 v[2:3], v[6:7], v[2:3]
	v_cvt_pk_bf16_f32 v38, v0, v1
	v_lshlrev_b32_e32 v7, 16, v4
	v_add_f32_e32 v0, v2, v3
	v_cvt_pk_bf16_f32 v39, v0, v1
	v_lshlrev_b32_e32 v6, 16, v8
	s_waitcnt vmcnt(1)
	v_mov_b32_e32 v3, v84
	v_mov_b32_e32 v42, v3
	s_waitcnt vmcnt(0)
	v_mov_b32_e32 v2, v100
	v_pk_mul_f32 v[40:41], v[2:3], v[6:7]
	v_mov_b32_e32 v43, v2
	v_sub_f32_e32 v0, v41, v40
	v_pk_mul_f32 v[2:3], v[42:43], v[6:7]
	v_cvt_pk_bf16_f32 v40, v0, v1
	v_and_b32_e32 v7, 0xffff0000, v4
	v_add_f32_e32 v0, v2, v3
	v_cvt_pk_bf16_f32 v41, v0, v1
	v_and_b32_e32 v6, 0xffff0000, v8
	v_and_b32_e32 v4, 0xffff0000, v9
	v_lshl_or_b32 v8, v69, 6, v70
	s_waitcnt vmcnt(0)
	v_mov_b32_e32 v3, v85
	v_mov_b32_e32 v2, v101
	v_pk_mul_f32 v[42:43], v[2:3], v[6:7]
	s_nop 0
	v_sub_f32_e32 v0, v43, v42
	v_mov_b32_e32 v42, v3
	v_mov_b32_e32 v43, v2
	v_pk_mul_f32 v[2:3], v[42:43], v[6:7]
	v_cvt_pk_bf16_f32 v58, v0, v1
	v_lshlrev_b32_e32 v7, 16, v5
	v_add_f32_e32 v0, v2, v3
	v_cvt_pk_bf16_f32 v59, v0, v1
	v_lshlrev_b32_e32 v6, 16, v9
	v_and_b32_e32 v5, 0xffff0000, v5
	v_mov_b32_e32 v9, v1
	v_lshlrev_b64 v[8:9], 1, v[8:9]
	v_lshl_add_u64 v[56:57], s[80:81], 0, v[8:9]
	v_lshl_add_u64 v[184:185], s[64:65], 0, v[8:9]
	v_mov_b32_e32 v8, v1
	v_mov_b32_e32 v9, v1
	s_waitcnt vmcnt(0)
	v_mov_b32_e32 v3, v86
	v_mov_b32_e32 v2, v102
	v_pk_mul_f32 v[42:43], v[2:3], v[6:7]
	s_nop 0
	v_sub_f32_e32 v0, v43, v42
	v_mov_b32_e32 v42, v3
	v_mov_b32_e32 v43, v2
	v_pk_mul_f32 v[2:3], v[42:43], v[6:7]
	v_cvt_pk_bf16_f32 v60, v0, v1
	s_nop 0
	v_add_f32_e32 v0, v2, v3
	v_cvt_pk_bf16_f32 v61, v0, v1
	v_mov_b32_e32 v19, v1
	s_waitcnt vmcnt(0)
; __device__ __forceinline__ u16 f2bf(float x) { return (u16)(cvtpk(x, 0.f) & 0xffffu); }
; __device__ __forceinline__ float bf2f(u16 x) { return __uint_as_float(((unsigned)x) << 16); }
; __device__ __forceinline__ int v_st(int k, int c) { const int kk = (k & ~0xC) | ((k & 4) << 1) | ((k & 8) >> 1); return ((kk >> 3) * 4 + (c >> 5)) * 512 + ((kk & 7) * 32 + (c & 31)) * 2; }
; __device__ __forceinline__ int v_rd_base(int lane) { return ((lane & 3) << 3) | (((lane >> 2) & 3) << 6) | (((lane >> 4) & 1) << 5) | (((lane >> 5) & 1) << 8); }
; #define SWRITE(S, b) do { *(bf16x8*)(V_lds + (b) * SHM_V + vst0) = S.vs0; *(bf16x8*)(V_lds + (b) * SHM_V + vst1) = S.vs1; int kc = sc * 2; \
;     *(bf16x8*)(K_lds + (b) * SHM_K + KSWZB(sr, kc)) = S.ks0; *(bf16x8*)(K_lds + (b) * SHM_K + KSWZB(32 + sr, kc)) = S.ks1; \
;     if constexpr (DQK == 192) *(bf16x8*)(K_lds + (b) * SHM_K + KSWZB(kr_row, 256 + kr_c * 2)) = S.ks2; } while (0)
; template <int DQK, int ldq, int ldk, int ldo> ...
;     ...
;         float a = bf2f((u16)x1[t]), b = bf2f((u16)x2[t]), c = cp[t], s = sp[t];
;         y1[t] = (short)f2bf(a * c - b * s); y2[t] = (short)f2bf(a * s + b * c);
;       }
;       qr[8 + hh] = y1; qr[10 + hh] = y2;
;     }
;   }
;   const int sr = tid >> 4, sc = (tid & 15) * 8, vst0 = v_st(sr, sc), vst1 = v_st(32 + sr, sc);
;   const int kr_row = tid >> 3, kr_c = (tid & 7) * 8;
;   const int vb0 = (int)(uintptr_t)V_lds + v_rd_base(lane);
;   struct Stg { bf16x8 vs0, vs1, ks0, ks1, ks2; } sa;
;     ...
;   const unsigned voff0 = sr * ldk + sc, voff1 = (32 + sr) * ldk + sc, kroff = kr_row * 64 + kr_c;
;     ...
;   f32x16 pA0, pA1; float mnA, alA; bf16x8 pa0, pa1, pa2, pa3; const int NT = seq / KVBLK;
;   SLOAD(sa, 0); SWRITE(sa, 0);
;   SLOAD(sa, KVBLK);
;   __syncthreads();
	v_mov_b32_e32 v3, v87
	v_mov_b32_e32 v2, v103
	v_pk_mul_f32 v[6:7], v[2:3], v[4:5]
	s_nop 0
	v_sub_f32_e32 v0, v7, v6
	v_mov_b32_e32 v6, v3
	v_mov_b32_e32 v7, v2
	v_pk_mul_f32 v[2:3], v[6:7], v[4:5]
	v_cvt_pk_bf16_f32 v62, v0, v1
	v_bfe_u32 v4, v65, 5, 2
	v_add_f32_e32 v0, v2, v3
	v_cvt_pk_bf16_f32 v63, v0, v1
	v_and_b32_e32 v0, 0xfffff0, v64
	v_lshlrev_b32_e32 v3, 1, v64
	v_and_or_b32 v0, v3, 8, v0
	v_and_b32_e32 v2, 0x78, v65
	v_lshrrev_b32_e32 v3, 1, v64
	v_lshrrev_b32_e32 v0, 1, v0
	v_and_b32_e32 v5, 3, v64
	v_or_b32_e32 v0, v0, v4
	v_and_or_b32 v3, v3, 4, v5
	v_lshlrev_b32_e32 v66, 1, v2
	v_lshlrev_b32_e32 v0, 9, v0
	v_lshlrev_b32_e32 v3, 6, v3
	v_and_b32_e32 v5, 48, v66
	v_add_u32_e32 v6, 32, v64
	v_or3_b32 v67, v0, v3, v5
	v_and_b32_e32 v0, 0xfffff0, v6
	v_lshlrev_b32_e32 v7, 1, v6
	v_and_or_b32 v0, v7, 8, v0
	v_lshrrev_b32_e32 v0, 1, v0
	v_or_b32_e32 v0, v0, v4
	v_lshlrev_b32_e32 v0, 9, v0
	v_or3_b32 v68, v0, v3, v5
	v_lshlrev_b32_e32 v3, 4, v23
	v_lshlrev_b32_e32 v0, 3, v22
	v_and_b32_e32 v3, 0xc0, v3
	v_lshlrev_b32_e32 v4, 1, v23
	v_and_or_b32 v3, v0, 24, v3
	v_and_b32_e32 v4, 32, v4
	v_and_b32_e32 v0, 0x100, v0
	v_or3_b32 v71, v3, v4, v0
	v_lshl_or_b32 v0, v64, 11, v2
	v_lshl_or_b32 v18, v6, 11, v2
	v_lshlrev_b64 v[6:7], 1, v[0:1]
	v_lshl_add_u64 v[42:43], s[8:9], 0, v[6:7]
	global_load_dwordx4 v[2:5], v[42:43], off offset:256
	v_lshlrev_b64 v[54:55], 1, v[18:19]
	v_lshl_add_u64 v[46:47], s[8:9], 0, v[54:55]
	v_add_u32_e32 v195, 16, v67
	global_load_dwordx4 v[18:21], v[46:47], off offset:256
	s_nop 0
	global_load_dwordx4 v[42:45], v[42:43], off
	s_nop 0
	global_load_dwordx4 v[46:49], v[46:47], off
	v_mul_lo_u32 v0, v64, s15
	s_add_u32 s8, s8, 0x40000
	global_load_dwordx4 v[50:53], v[56:57], off
	s_addc_u32 s9, s9, 0
	v_add_u32_e32 v183, s7, v71
	s_addk_i32 s7, 0x4000
	v_add_u32_e32 v215, s7, v71
	s_mov_b32 s7, 0x5040100
	v_add_u32_e32 v196, 16, v68
	v_perm_b32 v172, v14, v25, s7
	v_perm_b32 v173, v15, v27, s7
	s_or_b32 s0, s0, s6
	v_mov_b32_e32 v14, v1
	v_mov_b32_e32 v15, v1
	v_perm_b32 v164, v10, v24, s7
	v_perm_b32 v165, v11, v26, s7
	v_perm_b32 v166, v12, v28, s7
	v_perm_b32 v167, v13, v30, s7
	v_perm_b32 v168, v34, v32, s7
	v_perm_b32 v169, v38, v36, s7
	v_perm_b32 v170, v58, v40, s7
	v_perm_b32 v171, v62, v60, s7
	v_perm_b32 v174, v16, v29, s7
	v_perm_b32 v175, v17, v31, s7
	v_perm_b32 v176, v35, v33, s7
	v_perm_b32 v177, v39, v37, s7
	v_perm_b32 v178, v59, v41, s7
	v_perm_b32 v179, v63, v61, s7
	v_lshl_add_u64 v[186:187], s[0:1], 0, v[54:55]
	v_lshl_add_u64 v[188:189], s[0:1], 0, v[6:7]
	v_mov_b32_e32 v10, v1
	v_mov_b32_e32 v11, v1
	v_mov_b32_e32 v12, v1
	v_mov_b32_e32 v13, v1
	s_waitcnt vmcnt(4)
	ds_write_b128 v195, v[2:5]
	v_lshrrev_b32_e32 v2, 1, v23
	v_bitop3_b32 v2, v66, v2, s14 bitop3:0x78
	v_add3_u32 v197, v2, v0, 16
	v_mul_lo_u32 v0, v69, s15
	v_lshl_or_b32 v2, v70, 1, v191
	v_and_b32_e32 v3, 0x70, v23
	v_xad_u32 v0, v2, v3, v0
	v_lshl_add_u64 v[2:3], s[60:61], 0, v[6:7]
	global_load_dwordx4 v[144:147], v[2:3], off
	v_lshl_add_u64 v[2:3], s[60:61], 0, v[54:55]
	global_load_dwordx4 v[148:151], v[2:3], off
	v_lshl_add_u64 v[2:3], s[8:9], 0, v[6:7]
	global_load_dwordx4 v[152:155], v[2:3], off
	v_lshl_add_u64 v[2:3], s[8:9], 0, v[54:55]
	s_movk_i32 s8, 0x2000
	global_load_dwordx4 v[156:159], v[2:3], off
	v_add_co_u32_e32 v2, vcc, s8, v56
	v_add_u32_e32 v199, 16, v0
	s_nop 0
	v_addc_co_u32_e32 v3, vcc, 0, v57, vcc
	global_load_dwordx4 v[160:163], v[2:3], off
	v_and_b32_e32 v0, 0x70, v65
	s_movk_i32 s8, 0x60
	v_bitop3_b32 v204, v182, v0, s8 bitop3:0x36
	s_movk_i32 s8, 0x80
	v_bitop3_b32 v205, v182, v0, s8 bitop3:0x36
	s_movk_i32 s8, 0xa0
	v_bitop3_b32 v206, v182, v0, s8 bitop3:0x36
	s_movk_i32 s8, 0xc0
	v_bitop3_b32 v207, v182, v0, s8 bitop3:0x36
	s_movk_i32 s8, 0xe0
	v_bitop3_b32 v208, v182, v0, s8 bitop3:0x36
	s_movk_i32 s8, 0x100
	v_bitop3_b32 v209, v182, v0, s8 bitop3:0x36
	s_movk_i32 s8, 0x120
	v_bitop3_b32 v210, v182, v0, s8 bitop3:0x36
	s_movk_i32 s8, 0x140
	v_bitop3_b32 v212, v182, v0, s8 bitop3:0x36
	s_movk_i32 s8, 0x160
	s_waitcnt vmcnt(8)
	ds_write_b128 v196, v[18:21]
	s_waitcnt vmcnt(7)
	ds_write_b128 v197, v[42:45] offset:32768
	s_waitcnt vmcnt(6)
	ds_write_b128 v197, v[46:49] offset:45056
	s_waitcnt vmcnt(5)
	ds_write_b128 v199, v[50:53] offset:32768
	v_bitop3_b32 v201, v182, v0, 32 bitop3:0x36
	v_bitop3_b32 v202, v182, v0, 64 bitop3:0x36
	v_bitop3_b32 v213, v182, v0, s8 bitop3:0x36
	v_cmp_gt_u32_e64 s[8:9], 32, v22
	v_mov_b32_e32 v0, v1
	v_mov_b32_e32 v2, v1
	v_mov_b32_e32 v3, v1
	v_mov_b32_e32 v4, v1
	v_mov_b32_e32 v5, v1
	v_mov_b32_e32 v6, v1
	v_mov_b32_e32 v7, v1
	v_mov_b64_e32 v[62:63], v[14:15]
	v_mov_b64_e32 v[46:47], v[14:15]
	v_mov_b64_e32 v[30:31], v[14:15]
	v_mov_b64_e32 v[78:79], v[14:15]
	v_add_u32_e32 v198, 0x3000, v197
	v_mov_b64_e32 v[60:61], v[12:13]
	v_mov_b64_e32 v[58:59], v[10:11]
	v_mov_b64_e32 v[56:57], v[8:9]
	v_mov_b64_e32 v[54:55], v[6:7]
	v_mov_b64_e32 v[52:53], v[4:5]
	v_mov_b64_e32 v[50:51], v[2:3]
	v_mov_b64_e32 v[48:49], v[0:1]
	v_mov_b64_e32 v[44:45], v[12:13]
	v_mov_b64_e32 v[42:43], v[10:11]
	v_mov_b64_e32 v[40:41], v[8:9]
	v_mov_b64_e32 v[38:39], v[6:7]
	v_mov_b64_e32 v[36:37], v[4:5]
	v_mov_b64_e32 v[34:35], v[2:3]
	v_mov_b64_e32 v[32:33], v[0:1]
	v_mov_b64_e32 v[28:29], v[12:13]
	v_mov_b64_e32 v[26:27], v[10:11]
	v_mov_b64_e32 v[24:25], v[8:9]
	v_mov_b64_e32 v[22:23], v[6:7]
	v_mov_b64_e32 v[20:21], v[4:5]
	v_mov_b64_e32 v[18:19], v[2:3]
	v_mov_b64_e32 v[16:17], v[0:1]
	v_mov_b64_e32 v[76:77], v[12:13]
	v_mov_b64_e32 v[74:75], v[10:11]
	v_mov_b64_e32 v[72:73], v[8:9]
	v_mov_b64_e32 v[70:71], v[6:7]
	v_mov_b64_e32 v[68:69], v[4:5]
	v_mov_b64_e32 v[66:67], v[2:3]
	v_mov_b64_e32 v[64:65], v[0:1]
	s_waitcnt lgkmcnt(0)
	s_barrier
